# P6 residual loop: x loads as full 128-byte lines (8 rows per instruction) with a DPP row_ror:8 exchange back into the accumulator layout
# speedup vs baseline: 1.0099x; 1.0012x over previous
;     __device__ __forceinline__ void fused(f32x4 (&acc)[2][2][4][2], const Unit& u, int wr, int wc, int fr, int fq, PG8_LAS unsigned char* lds, int wid, int lane) const {
;     ...
; #pragma unroll
;             for (int ai = 0; ai < 2; ++ai)
; #pragma unroll
;                 for (int m = 0; m < 4; ++m) { const int r = ai * HALF + wr * 64 + m * 16 + fr; const float rs = S[r]; const size_t off = (size_t)(row_off + u.pm * BM + r) * DM + col0;
; #pragma unroll
;                     for (int bj = 0; bj < 2; ++bj)
; #pragma unroll
;                         for (int n = 0; n < 2; ++n) { const f32x4 bs = __builtin_nontemporal_load((const f32x4*)(base + off + bj * HALF + n * 16)); acc[ai][bj][m][n] = bs + acc[ai][bj][m][n] * rs * g[bj][n]; }
;                     asm volatile("" : "+v"(acc[ai][0][m][0]), "+v"(acc[ai][0][m][1]), "+v"(acc[ai][1][m][0]), "+v"(acc[ai][1][m][1]));
;                     if (m & 1) asm volatile("" ::: "memory"); }
.LBB0_790:
	s_or_b64 exec, exec, s[54:55]
	v_and_b32_e32 v210, 8, v195
	v_mul_i32_i24_e32 v208, 0xfffff008, v210
	v_ashrrev_i32_e32 v209, 31, v208
	s_lshl_b32 s26, s33, 5
	s_lshl_b32 s27, s46, 8
	s_or_b32 s26, s27, s26
	v_lshrrev_b32_e32 v128, 2, v138
	v_and_or_b32 v166, v128, 12, s26
	s_lshl_b32 s26, s18, 12
	s_add_i32 s52, s19, s26
	s_ashr_i32 s53, s52, 31
	s_lshl_b64 s[52:53], s[52:53], 2
	s_add_u32 s19, s14, s52
	s_addc_u32 s26, s15, s53
	s_add_u32 s52, s19, 0x1c0000
	s_addc_u32 s53, s26, 0
	s_lshl_b32 s18, s18, 14
	s_lshl_b32 s19, s37, 8
	s_add_i32 s19, s19, s18
	v_add_u32_e32 v178, s19, v149
	v_ashrrev_i32_e32 v179, 31, v178
	v_ashrrev_i32_e32 v167, 31, v166
	v_lshlrev_b64 v[128:129], 12, v[178:179]
	v_lshlrev_b64 v[146:147], 2, v[166:167]
	v_lshl_add_u64 v[128:129], s[48:49], 0, v[128:129]
	s_waitcnt lgkmcnt(0)
	s_barrier
	v_lshl_add_u64 v[136:137], s[52:53], 0, v[146:147]
	v_lshl_add_u64 v[158:159], v[128:129], 0, v[146:147]
	v_lshl_add_u64 v[214:215], v[158:159], 0, v[208:209]
	v_lshl_add_u64 v[212:213], v[214:215], 0, s[42:43]
	global_load_dwordx4 v[154:157], v[214:215], off nt
	global_load_dwordx4 v[168:171], v[212:213], off nt
	global_load_dwordx4 v[172:175], v[214:215], off offset:512 nt
	global_load_dwordx4 v[180:183], v[212:213], off offset:512 nt
	global_load_dwordx4 v[132:135], v[136:137], off
	s_waitcnt lgkmcnt(0)
	global_load_dwordx4 v[128:131], v[136:137], off offset:64
	global_load_dwordx4 v[140:143], v[136:137], off offset:512
	s_nop 0
	global_load_dwordx4 v[136:139], v[136:137], off offset:576
	s_nop 0
	v_lshl_add_u32 v160, v149, 2, 0
	ds_read_b32 v158, v160 offset:4096
	v_add_u32_e32 v176, 16, v178
	v_ashrrev_i32_e32 v177, 31, v176
	s_waitcnt lgkmcnt(0)
	v_pk_mul_f32 v[124:125], v[124:125], v[158:159] op_sel_hi:[1,0]
	v_pk_mul_f32 v[126:127], v[126:127], v[158:159] op_sel_hi:[1,0]
	v_pk_mul_f32 v[120:121], v[120:121], v[158:159] op_sel_hi:[1,0]
	v_pk_mul_f32 v[122:123], v[122:123], v[158:159] op_sel_hi:[1,0]
	v_pk_mul_f32 v[116:117], v[116:117], v[158:159] op_sel_hi:[1,0]
	v_pk_mul_f32 v[118:119], v[118:119], v[158:159] op_sel_hi:[1,0]
	v_pk_mul_f32 v[112:113], v[112:113], v[158:159] op_sel_hi:[1,0]
	v_pk_mul_f32 v[114:115], v[114:115], v[158:159] op_sel_hi:[1,0]
	v_lshlrev_b64 v[158:159], 12, v[176:177]
	v_lshl_add_u64 v[158:159], s[48:49], 0, v[158:159]
	v_lshl_add_u64 v[158:159], v[158:159], 0, v[146:147]
	s_waitcnt vmcnt(0)
	v_mov_b32_e32 v204, v154
	v_mov_b32_e32 v205, v155
	v_mov_b32_e32 v206, v156
	v_mov_b32_e32 v207, v157
	v_mov_b32_dpp v154, v168 row_ror:8 row_mask:0xf bank_mask:0xc
	v_mov_b32_dpp v155, v169 row_ror:8 row_mask:0xf bank_mask:0xc
	v_mov_b32_dpp v156, v170 row_ror:8 row_mask:0xf bank_mask:0xc
	v_mov_b32_dpp v157, v171 row_ror:8 row_mask:0xf bank_mask:0xc
	v_mov_b32_dpp v168, v204 row_ror:8 row_mask:0xf bank_mask:0x3
	v_mov_b32_dpp v169, v205 row_ror:8 row_mask:0xf bank_mask:0x3
	v_mov_b32_dpp v170, v206 row_ror:8 row_mask:0xf bank_mask:0x3
	v_mov_b32_dpp v171, v207 row_ror:8 row_mask:0xf bank_mask:0x3
	v_mov_b32_e32 v204, v172
	v_mov_b32_e32 v205, v173
	v_mov_b32_e32 v206, v174
	v_mov_b32_e32 v207, v175
	v_mov_b32_dpp v172, v180 row_ror:8 row_mask:0xf bank_mask:0xc
	v_mov_b32_dpp v173, v181 row_ror:8 row_mask:0xf bank_mask:0xc
	v_mov_b32_dpp v174, v182 row_ror:8 row_mask:0xf bank_mask:0xc
	v_mov_b32_dpp v175, v183 row_ror:8 row_mask:0xf bank_mask:0xc
	v_mov_b32_dpp v180, v204 row_ror:8 row_mask:0xf bank_mask:0x3
	v_mov_b32_dpp v181, v205 row_ror:8 row_mask:0xf bank_mask:0x3
	v_mov_b32_dpp v182, v206 row_ror:8 row_mask:0xf bank_mask:0x3
	v_mov_b32_dpp v183, v207 row_ror:8 row_mask:0xf bank_mask:0x3
	v_pk_fma_f32 v[126:127], v[134:135], v[126:127], v[156:157]
	v_pk_fma_f32 v[124:125], v[132:133], v[124:125], v[154:155]
	v_pk_fma_f32 v[122:123], v[130:131], v[122:123], v[170:171]
	v_pk_fma_f32 v[120:121], v[128:129], v[120:121], v[168:169]
	v_pk_fma_f32 v[118:119], v[142:143], v[118:119], v[174:175]
	v_pk_fma_f32 v[116:117], v[140:141], v[116:117], v[172:173]
	v_pk_fma_f32 v[114:115], v[138:139], v[114:115], v[182:183]
	v_pk_fma_f32 v[112:113], v[136:137], v[112:113], v[180:181]
	v_add_u32_e32 v168, 32, v178
	v_lshl_add_u64 v[214:215], v[158:159], 0, v[208:209]
	v_lshl_add_u64 v[212:213], v[214:215], 0, s[42:43]
	global_load_dwordx4 v[154:157], v[214:215], off nt
	global_load_dwordx4 v[170:173], v[212:213], off nt
	global_load_dwordx4 v[180:183], v[214:215], off offset:512 nt
	global_load_dwordx4 v[188:191], v[212:213], off offset:512 nt
	ds_read_b32 v158, v160 offset:4160
	v_ashrrev_i32_e32 v169, 31, v168
	v_lshlrev_b64 v[174:175], 12, v[168:169]
	v_lshl_add_u64 v[174:175], s[48:49], 0, v[174:175]
	v_lshl_add_u64 v[192:193], v[174:175], 0, v[146:147]
	s_waitcnt lgkmcnt(0)
	v_pk_mul_f32 v[108:109], v[108:109], v[158:159] op_sel_hi:[1,0]
	v_pk_mul_f32 v[110:111], v[110:111], v[158:159] op_sel_hi:[1,0]
	v_pk_mul_f32 v[104:105], v[104:105], v[158:159] op_sel_hi:[1,0]
	v_pk_mul_f32 v[106:107], v[106:107], v[158:159] op_sel_hi:[1,0]
	v_pk_mul_f32 v[100:101], v[100:101], v[158:159] op_sel_hi:[1,0]
	v_pk_mul_f32 v[102:103], v[102:103], v[158:159] op_sel_hi:[1,0]
	v_pk_mul_f32 v[96:97], v[96:97], v[158:159] op_sel_hi:[1,0]
	v_pk_mul_f32 v[98:99], v[98:99], v[158:159] op_sel_hi:[1,0]
	v_mul_f32_e32 v145, v125, v125
	v_mul_f32_e32 v149, v123, v123
	v_fmac_f32_e32 v145, v124, v124
	v_fmac_f32_e32 v149, v122, v122
	v_mul_f32_e32 v187, v113, v113
	v_fmac_f32_e32 v187, v112, v112
	s_waitcnt vmcnt(2)
;     __device__ __forceinline__ void fused(f32x4 (&acc)[2][2][4][2], const Unit& u, int wr, int wc, int fr, int fq, PG8_LAS unsigned char* lds, int wid, int lane) const {
;     ...
; #pragma unroll
;             for (int ai = 0; ai < 2; ++ai)
; #pragma unroll
;                 for (int m = 0; m < 4; ++m) { const int r = ai * HALF + wr * 64 + m * 16 + fr; const float rs = S[r]; const size_t off = (size_t)(row_off + u.pm * BM + r) * DM + col0;
; #pragma unroll
;                     for (int bj = 0; bj < 2; ++bj)
; #pragma unroll
;                         for (int n = 0; n < 2; ++n) { const f32x4 bs = __builtin_nontemporal_load((const f32x4*)(base + off + bj * HALF + n * 16)); acc[ai][bj][m][n] = bs + acc[ai][bj][m][n] * rs * g[bj][n]; }
;                     asm volatile("" : "+v"(acc[ai][0][m][0]), "+v"(acc[ai][0][m][1]), "+v"(acc[ai][1][m][0]), "+v"(acc[ai][1][m][1]));
;                     if (m & 1) asm volatile("" ::: "memory"); }
	v_mov_b32_e32 v204, v154
	v_mov_b32_e32 v205, v155
	v_mov_b32_e32 v206, v156
	v_mov_b32_e32 v207, v157
	v_mov_b32_dpp v154, v170 row_ror:8 row_mask:0xf bank_mask:0xc
	v_mov_b32_dpp v155, v171 row_ror:8 row_mask:0xf bank_mask:0xc
	v_mov_b32_dpp v156, v172 row_ror:8 row_mask:0xf bank_mask:0xc
	v_mov_b32_dpp v157, v173 row_ror:8 row_mask:0xf bank_mask:0xc
	v_mov_b32_dpp v170, v204 row_ror:8 row_mask:0xf bank_mask:0x3
	v_mov_b32_dpp v171, v205 row_ror:8 row_mask:0xf bank_mask:0x3
	v_mov_b32_dpp v172, v206 row_ror:8 row_mask:0xf bank_mask:0x3
	v_mov_b32_dpp v173, v207 row_ror:8 row_mask:0xf bank_mask:0x3
	v_pk_fma_f32 v[110:111], v[134:135], v[110:111], v[156:157]
	v_pk_fma_f32 v[108:109], v[132:133], v[108:109], v[154:155]
	s_waitcnt vmcnt(2)
	v_pk_fma_f32 v[106:107], v[130:131], v[106:107], v[172:173]
	v_pk_fma_f32 v[104:105], v[128:129], v[104:105], v[170:171]
	s_waitcnt vmcnt(0)
	v_mov_b32_e32 v204, v180
	v_mov_b32_e32 v205, v181
	v_mov_b32_e32 v206, v182
	v_mov_b32_e32 v207, v183
	v_mov_b32_dpp v180, v188 row_ror:8 row_mask:0xf bank_mask:0xc
	v_mov_b32_dpp v181, v189 row_ror:8 row_mask:0xf bank_mask:0xc
	v_mov_b32_dpp v182, v190 row_ror:8 row_mask:0xf bank_mask:0xc
	v_mov_b32_dpp v183, v191 row_ror:8 row_mask:0xf bank_mask:0xc
	v_mov_b32_dpp v188, v204 row_ror:8 row_mask:0xf bank_mask:0x3
	v_mov_b32_dpp v189, v205 row_ror:8 row_mask:0xf bank_mask:0x3
	v_mov_b32_dpp v190, v206 row_ror:8 row_mask:0xf bank_mask:0x3
	v_mov_b32_dpp v191, v207 row_ror:8 row_mask:0xf bank_mask:0x3
	v_pk_fma_f32 v[102:103], v[142:143], v[102:103], v[182:183]
	v_pk_fma_f32 v[100:101], v[140:141], v[100:101], v[180:181]
	s_waitcnt vmcnt(0)
	v_pk_fma_f32 v[98:99], v[138:139], v[98:99], v[190:191]
	v_pk_fma_f32 v[96:97], v[136:137], v[96:97], v[188:189]
	v_add_u32_e32 v170, 48, v178
	v_lshl_add_u64 v[214:215], v[192:193], 0, v[208:209]
	v_lshl_add_u64 v[212:213], v[214:215], 0, s[42:43]
	global_load_dwordx4 v[154:157], v[214:215], off nt
	global_load_dwordx4 v[172:175], v[212:213], off nt
	global_load_dwordx4 v[180:183], v[214:215], off offset:512 nt
	global_load_dwordx4 v[188:191], v[212:213], off offset:512 nt
	ds_read_b32 v158, v160 offset:4224
	v_ashrrev_i32_e32 v171, 31, v170
	v_lshlrev_b64 v[192:193], 12, v[170:171]
	v_lshl_add_u64 v[192:193], s[48:49], 0, v[192:193]
	v_lshl_add_u64 v[192:193], v[192:193], 0, v[146:147]
	s_waitcnt lgkmcnt(0)
	v_pk_mul_f32 v[92:93], v[92:93], v[158:159] op_sel_hi:[1,0]
	v_pk_mul_f32 v[94:95], v[94:95], v[158:159] op_sel_hi:[1,0]
	v_pk_mul_f32 v[88:89], v[88:89], v[158:159] op_sel_hi:[1,0]
	v_pk_mul_f32 v[90:91], v[90:91], v[158:159] op_sel_hi:[1,0]
	v_pk_mul_f32 v[84:85], v[84:85], v[158:159] op_sel_hi:[1,0]
	v_pk_mul_f32 v[86:87], v[86:87], v[158:159] op_sel_hi:[1,0]
	v_pk_mul_f32 v[80:81], v[80:81], v[158:159] op_sel_hi:[1,0]
	v_pk_mul_f32 v[82:83], v[82:83], v[158:159] op_sel_hi:[1,0]
	s_waitcnt vmcnt(2)
	v_mov_b32_e32 v204, v154
	v_mov_b32_e32 v205, v155
	v_mov_b32_e32 v206, v156
	v_mov_b32_e32 v207, v157
	v_mov_b32_dpp v154, v172 row_ror:8 row_mask:0xf bank_mask:0xc
	v_mov_b32_dpp v155, v173 row_ror:8 row_mask:0xf bank_mask:0xc
	v_mov_b32_dpp v156, v174 row_ror:8 row_mask:0xf bank_mask:0xc
	v_mov_b32_dpp v157, v175 row_ror:8 row_mask:0xf bank_mask:0xc
	v_mov_b32_dpp v172, v204 row_ror:8 row_mask:0xf bank_mask:0x3
	v_mov_b32_dpp v173, v205 row_ror:8 row_mask:0xf bank_mask:0x3
	v_mov_b32_dpp v174, v206 row_ror:8 row_mask:0xf bank_mask:0x3
	v_mov_b32_dpp v175, v207 row_ror:8 row_mask:0xf bank_mask:0x3
	v_pk_fma_f32 v[94:95], v[134:135], v[94:95], v[156:157]
	v_pk_fma_f32 v[92:93], v[132:133], v[92:93], v[154:155]
	s_waitcnt vmcnt(2)
	v_pk_fma_f32 v[90:91], v[130:131], v[90:91], v[174:175]
	v_pk_fma_f32 v[88:89], v[128:129], v[88:89], v[172:173]
	s_waitcnt vmcnt(0)
	v_mov_b32_e32 v204, v180
	v_mov_b32_e32 v205, v181
	v_mov_b32_e32 v206, v182
	v_mov_b32_e32 v207, v183
	v_mov_b32_dpp v180, v188 row_ror:8 row_mask:0xf bank_mask:0xc
	v_mov_b32_dpp v181, v189 row_ror:8 row_mask:0xf bank_mask:0xc
	v_mov_b32_dpp v182, v190 row_ror:8 row_mask:0xf bank_mask:0xc
	v_mov_b32_dpp v183, v191 row_ror:8 row_mask:0xf bank_mask:0xc
	v_mov_b32_dpp v188, v204 row_ror:8 row_mask:0xf bank_mask:0x3
	v_mov_b32_dpp v189, v205 row_ror:8 row_mask:0xf bank_mask:0x3
	v_mov_b32_dpp v190, v206 row_ror:8 row_mask:0xf bank_mask:0x3
	v_mov_b32_dpp v191, v207 row_ror:8 row_mask:0xf bank_mask:0x3
	v_pk_fma_f32 v[86:87], v[142:143], v[86:87], v[182:183]
	v_pk_fma_f32 v[84:85], v[140:141], v[84:85], v[180:181]
	s_waitcnt vmcnt(0)
	v_pk_fma_f32 v[82:83], v[138:139], v[82:83], v[190:191]
	v_pk_fma_f32 v[80:81], v[136:137], v[80:81], v[188:189]
	v_add_u32_e32 v172, 0x80, v178
	v_lshl_add_u64 v[214:215], v[192:193], 0, v[208:209]
	v_lshl_add_u64 v[212:213], v[214:215], 0, s[42:43]
	global_load_dwordx4 v[154:157], v[214:215], off nt
	global_load_dwordx4 v[180:183], v[212:213], off nt
	global_load_dwordx4 v[188:191], v[214:215], off offset:512 nt
	global_load_dwordx4 v[196:199], v[212:213], off offset:512 nt
	ds_read_b32 v158, v160 offset:4288
	v_ashrrev_i32_e32 v173, 31, v172
	v_lshlrev_b64 v[174:175], 12, v[172:173]
	v_lshl_add_u64 v[174:175], s[48:49], 0, v[174:175]
	v_lshl_add_u64 v[174:175], v[174:175], 0, v[146:147]
	s_waitcnt lgkmcnt(0)
	v_pk_mul_f32 v[76:77], v[76:77], v[158:159] op_sel_hi:[1,0]
	v_pk_mul_f32 v[78:79], v[78:79], v[158:159] op_sel_hi:[1,0]
	v_pk_mul_f32 v[72:73], v[72:73], v[158:159] op_sel_hi:[1,0]
	v_pk_mul_f32 v[74:75], v[74:75], v[158:159] op_sel_hi:[1,0]
	v_pk_mul_f32 v[68:69], v[68:69], v[158:159] op_sel_hi:[1,0]
	v_pk_mul_f32 v[70:71], v[70:71], v[158:159] op_sel_hi:[1,0]
	v_pk_mul_f32 v[64:65], v[64:65], v[158:159] op_sel_hi:[1,0]
	v_pk_mul_f32 v[66:67], v[66:67], v[158:159] op_sel_hi:[1,0]
	s_waitcnt vmcnt(2)
;     __device__ __forceinline__ void fused(f32x4 (&acc)[2][2][4][2], const Unit& u, int wr, int wc, int fr, int fq, PG8_LAS unsigned char* lds, int wid, int lane) const {
;     ...
; #pragma unroll
;             for (int ai = 0; ai < 2; ++ai)
; #pragma unroll
;                 for (int m = 0; m < 4; ++m) { const int r = ai * HALF + wr * 64 + m * 16 + fr; const float rs = S[r]; const size_t off = (size_t)(row_off + u.pm * BM + r) * DM + col0;
; #pragma unroll
;                     for (int bj = 0; bj < 2; ++bj)
; #pragma unroll
;                         for (int n = 0; n < 2; ++n) { const f32x4 bs = __builtin_nontemporal_load((const f32x4*)(base + off + bj * HALF + n * 16)); acc[ai][bj][m][n] = bs + acc[ai][bj][m][n] * rs * g[bj][n]; }
;                     asm volatile("" : "+v"(acc[ai][0][m][0]), "+v"(acc[ai][0][m][1]), "+v"(acc[ai][1][m][0]), "+v"(acc[ai][1][m][1]));
;                     if (m & 1) asm volatile("" ::: "memory"); }
	v_mov_b32_e32 v204, v154
	v_mov_b32_e32 v205, v155
	v_mov_b32_e32 v206, v156
	v_mov_b32_e32 v207, v157
	v_mov_b32_dpp v154, v180 row_ror:8 row_mask:0xf bank_mask:0xc
	v_mov_b32_dpp v155, v181 row_ror:8 row_mask:0xf bank_mask:0xc
	v_mov_b32_dpp v156, v182 row_ror:8 row_mask:0xf bank_mask:0xc
	v_mov_b32_dpp v157, v183 row_ror:8 row_mask:0xf bank_mask:0xc
	v_mov_b32_dpp v180, v204 row_ror:8 row_mask:0xf bank_mask:0x3
	v_mov_b32_dpp v181, v205 row_ror:8 row_mask:0xf bank_mask:0x3
	v_mov_b32_dpp v182, v206 row_ror:8 row_mask:0xf bank_mask:0x3
	v_mov_b32_dpp v183, v207 row_ror:8 row_mask:0xf bank_mask:0x3
	v_pk_fma_f32 v[78:79], v[134:135], v[78:79], v[156:157]
	v_pk_fma_f32 v[76:77], v[132:133], v[76:77], v[154:155]
	s_waitcnt vmcnt(2)
	v_pk_fma_f32 v[74:75], v[130:131], v[74:75], v[182:183]
	v_pk_fma_f32 v[72:73], v[128:129], v[72:73], v[180:181]
	s_waitcnt vmcnt(0)
	v_mov_b32_e32 v204, v188
	v_mov_b32_e32 v205, v189
	v_mov_b32_e32 v206, v190
	v_mov_b32_e32 v207, v191
	v_mov_b32_dpp v188, v196 row_ror:8 row_mask:0xf bank_mask:0xc
	v_mov_b32_dpp v189, v197 row_ror:8 row_mask:0xf bank_mask:0xc
	v_mov_b32_dpp v190, v198 row_ror:8 row_mask:0xf bank_mask:0xc
	v_mov_b32_dpp v191, v199 row_ror:8 row_mask:0xf bank_mask:0xc
	v_mov_b32_dpp v196, v204 row_ror:8 row_mask:0xf bank_mask:0x3
	v_mov_b32_dpp v197, v205 row_ror:8 row_mask:0xf bank_mask:0x3
	v_mov_b32_dpp v198, v206 row_ror:8 row_mask:0xf bank_mask:0x3
	v_mov_b32_dpp v199, v207 row_ror:8 row_mask:0xf bank_mask:0x3
	v_pk_fma_f32 v[70:71], v[142:143], v[70:71], v[190:191]
	v_pk_fma_f32 v[68:69], v[140:141], v[68:69], v[188:189]
	s_waitcnt vmcnt(0)
	v_pk_fma_f32 v[66:67], v[138:139], v[66:67], v[198:199]
	v_pk_fma_f32 v[64:65], v[136:137], v[64:65], v[196:197]
	s_nop 0
	v_lshl_add_u64 v[214:215], v[174:175], 0, v[208:209]
	v_lshl_add_u64 v[212:213], v[214:215], 0, s[42:43]
	global_load_dwordx4 v[154:157], v[214:215], off nt
	global_load_dwordx4 v[180:183], v[212:213], off nt
	global_load_dwordx4 v[188:191], v[214:215], off offset:512 nt
	global_load_dwordx4 v[196:199], v[212:213], off offset:512 nt
	ds_read_b32 v158, v160 offset:4608
	v_add_u32_e32 v174, 0x90, v178
	v_ashrrev_i32_e32 v175, 31, v174
	v_lshlrev_b64 v[192:193], 12, v[174:175]
	v_lshl_add_u64 v[192:193], s[48:49], 0, v[192:193]
	s_waitcnt lgkmcnt(0)
	v_pk_mul_f32 v[60:61], v[60:61], v[158:159] op_sel_hi:[1,0]
	v_pk_mul_f32 v[62:63], v[62:63], v[158:159] op_sel_hi:[1,0]
	v_pk_mul_f32 v[56:57], v[56:57], v[158:159] op_sel_hi:[1,0]
	v_pk_mul_f32 v[58:59], v[58:59], v[158:159] op_sel_hi:[1,0]
	v_pk_mul_f32 v[52:53], v[52:53], v[158:159] op_sel_hi:[1,0]
	v_pk_mul_f32 v[54:55], v[54:55], v[158:159] op_sel_hi:[1,0]
	v_pk_mul_f32 v[48:49], v[48:49], v[158:159] op_sel_hi:[1,0]
	v_pk_mul_f32 v[50:51], v[50:51], v[158:159] op_sel_hi:[1,0]
	v_lshl_add_u64 v[192:193], v[192:193], 0, v[146:147]
	s_waitcnt vmcnt(2)
	v_mov_b32_e32 v204, v154
	v_mov_b32_e32 v205, v155
	v_mov_b32_e32 v206, v156
	v_mov_b32_e32 v207, v157
	v_mov_b32_dpp v154, v180 row_ror:8 row_mask:0xf bank_mask:0xc
	v_mov_b32_dpp v155, v181 row_ror:8 row_mask:0xf bank_mask:0xc
	v_mov_b32_dpp v156, v182 row_ror:8 row_mask:0xf bank_mask:0xc
	v_mov_b32_dpp v157, v183 row_ror:8 row_mask:0xf bank_mask:0xc
	v_mov_b32_dpp v180, v204 row_ror:8 row_mask:0xf bank_mask:0x3
	v_mov_b32_dpp v181, v205 row_ror:8 row_mask:0xf bank_mask:0x3
	v_mov_b32_dpp v182, v206 row_ror:8 row_mask:0xf bank_mask:0x3
	v_mov_b32_dpp v183, v207 row_ror:8 row_mask:0xf bank_mask:0x3
	v_pk_fma_f32 v[62:63], v[134:135], v[62:63], v[156:157]
	v_pk_fma_f32 v[60:61], v[132:133], v[60:61], v[154:155]
	s_waitcnt vmcnt(2)
	v_pk_fma_f32 v[58:59], v[130:131], v[58:59], v[182:183]
	v_pk_fma_f32 v[56:57], v[128:129], v[56:57], v[180:181]
	s_waitcnt vmcnt(0)
	v_mov_b32_e32 v204, v188
	v_mov_b32_e32 v205, v189
	v_mov_b32_e32 v206, v190
	v_mov_b32_e32 v207, v191
	v_mov_b32_dpp v188, v196 row_ror:8 row_mask:0xf bank_mask:0xc
	v_mov_b32_dpp v189, v197 row_ror:8 row_mask:0xf bank_mask:0xc
	v_mov_b32_dpp v190, v198 row_ror:8 row_mask:0xf bank_mask:0xc
	v_mov_b32_dpp v191, v199 row_ror:8 row_mask:0xf bank_mask:0xc
	v_mov_b32_dpp v196, v204 row_ror:8 row_mask:0xf bank_mask:0x3
	v_mov_b32_dpp v197, v205 row_ror:8 row_mask:0xf bank_mask:0x3
	v_mov_b32_dpp v198, v206 row_ror:8 row_mask:0xf bank_mask:0x3
	v_mov_b32_dpp v199, v207 row_ror:8 row_mask:0xf bank_mask:0x3
	v_pk_fma_f32 v[54:55], v[142:143], v[54:55], v[190:191]
	v_pk_fma_f32 v[52:53], v[140:141], v[52:53], v[188:189]
	s_waitcnt vmcnt(0)
	v_pk_fma_f32 v[50:51], v[138:139], v[50:51], v[198:199]
	v_pk_fma_f32 v[48:49], v[136:137], v[48:49], v[196:197]
	v_add_u32_e32 v180, 0xa0, v178
	v_lshl_add_u64 v[214:215], v[192:193], 0, v[208:209]
	v_lshl_add_u64 v[212:213], v[214:215], 0, s[42:43]
	global_load_dwordx4 v[154:157], v[214:215], off nt
	global_load_dwordx4 v[188:191], v[212:213], off nt
	global_load_dwordx4 v[196:199], v[214:215], off offset:512 nt
	global_load_dwordx4 v[200:203], v[212:213], off offset:512 nt
	ds_read_b32 v158, v160 offset:4672
	v_ashrrev_i32_e32 v181, 31, v180
	v_lshlrev_b64 v[182:183], 12, v[180:181]
	v_lshl_add_u64 v[182:183], s[48:49], 0, v[182:183]
	v_lshl_add_u64 v[182:183], v[182:183], 0, v[146:147]
	s_waitcnt lgkmcnt(0)
	v_pk_mul_f32 v[44:45], v[44:45], v[158:159] op_sel_hi:[1,0]
	v_pk_mul_f32 v[46:47], v[46:47], v[158:159] op_sel_hi:[1,0]
	v_pk_mul_f32 v[40:41], v[40:41], v[158:159] op_sel_hi:[1,0]
	v_pk_mul_f32 v[42:43], v[42:43], v[158:159] op_sel_hi:[1,0]
	v_pk_mul_f32 v[36:37], v[36:37], v[158:159] op_sel_hi:[1,0]
	v_pk_mul_f32 v[38:39], v[38:39], v[158:159] op_sel_hi:[1,0]
	v_pk_mul_f32 v[32:33], v[32:33], v[158:159] op_sel_hi:[1,0]
	v_pk_mul_f32 v[34:35], v[34:35], v[158:159] op_sel_hi:[1,0]
	s_waitcnt vmcnt(2)
;     __device__ __forceinline__ void fused(f32x4 (&acc)[2][2][4][2], const Unit& u, int wr, int wc, int fr, int fq, PG8_LAS unsigned char* lds, int wid, int lane) const {
;     ...
; #pragma unroll
;             for (int ai = 0; ai < 2; ++ai)
; #pragma unroll
;                 for (int m = 0; m < 4; ++m) { const int r = ai * HALF + wr * 64 + m * 16 + fr; const float rs = S[r]; const size_t off = (size_t)(row_off + u.pm * BM + r) * DM + col0;
; #pragma unroll
;                     for (int bj = 0; bj < 2; ++bj)
; #pragma unroll
;                         for (int n = 0; n < 2; ++n) { const f32x4 bs = __builtin_nontemporal_load((const f32x4*)(base + off + bj * HALF + n * 16)); acc[ai][bj][m][n] = bs + acc[ai][bj][m][n] * rs * g[bj][n]; }
;                     asm volatile("" : "+v"(acc[ai][0][m][0]), "+v"(acc[ai][0][m][1]), "+v"(acc[ai][1][m][0]), "+v"(acc[ai][1][m][1]));
;                     if (m & 1) asm volatile("" ::: "memory"); }
	v_mov_b32_e32 v204, v154
	v_mov_b32_e32 v205, v155
	v_mov_b32_e32 v206, v156
	v_mov_b32_e32 v207, v157
	v_mov_b32_dpp v154, v188 row_ror:8 row_mask:0xf bank_mask:0xc
	v_mov_b32_dpp v155, v189 row_ror:8 row_mask:0xf bank_mask:0xc
	v_mov_b32_dpp v156, v190 row_ror:8 row_mask:0xf bank_mask:0xc
	v_mov_b32_dpp v157, v191 row_ror:8 row_mask:0xf bank_mask:0xc
	v_mov_b32_dpp v188, v204 row_ror:8 row_mask:0xf bank_mask:0x3
	v_mov_b32_dpp v189, v205 row_ror:8 row_mask:0xf bank_mask:0x3
	v_mov_b32_dpp v190, v206 row_ror:8 row_mask:0xf bank_mask:0x3
	v_mov_b32_dpp v191, v207 row_ror:8 row_mask:0xf bank_mask:0x3
	v_pk_fma_f32 v[46:47], v[134:135], v[46:47], v[156:157]
	v_pk_fma_f32 v[44:45], v[132:133], v[44:45], v[154:155]
	s_waitcnt vmcnt(2)
	v_pk_fma_f32 v[42:43], v[130:131], v[42:43], v[190:191]
	v_pk_fma_f32 v[40:41], v[128:129], v[40:41], v[188:189]
	s_waitcnt vmcnt(0)
	v_mov_b32_e32 v204, v196
	v_mov_b32_e32 v205, v197
	v_mov_b32_e32 v206, v198
	v_mov_b32_e32 v207, v199
	v_mov_b32_dpp v196, v200 row_ror:8 row_mask:0xf bank_mask:0xc
	v_mov_b32_dpp v197, v201 row_ror:8 row_mask:0xf bank_mask:0xc
	v_mov_b32_dpp v198, v202 row_ror:8 row_mask:0xf bank_mask:0xc
	v_mov_b32_dpp v199, v203 row_ror:8 row_mask:0xf bank_mask:0xc
	v_mov_b32_dpp v200, v204 row_ror:8 row_mask:0xf bank_mask:0x3
	v_mov_b32_dpp v201, v205 row_ror:8 row_mask:0xf bank_mask:0x3
	v_mov_b32_dpp v202, v206 row_ror:8 row_mask:0xf bank_mask:0x3
	v_mov_b32_dpp v203, v207 row_ror:8 row_mask:0xf bank_mask:0x3
	v_pk_fma_f32 v[38:39], v[142:143], v[38:39], v[198:199]
	v_pk_fma_f32 v[36:37], v[140:141], v[36:37], v[196:197]
	s_waitcnt vmcnt(0)
	v_pk_fma_f32 v[34:35], v[138:139], v[34:35], v[202:203]
	v_pk_fma_f32 v[32:33], v[136:137], v[32:33], v[200:201]
	s_nop 0
	v_lshl_add_u64 v[214:215], v[182:183], 0, v[208:209]
	v_lshl_add_u64 v[212:213], v[214:215], 0, s[42:43]
	global_load_dwordx4 v[154:157], v[214:215], off nt
	global_load_dwordx4 v[188:191], v[212:213], off nt
	global_load_dwordx4 v[196:199], v[214:215], off offset:512 nt
	global_load_dwordx4 v[200:203], v[212:213], off offset:512 nt
	ds_read_b32 v158, v160 offset:4736
	v_add_u32_e32 v182, 0xb0, v178
	v_ashrrev_i32_e32 v183, 31, v182
	v_lshlrev_b64 v[192:193], 12, v[182:183]
	v_lshl_add_u64 v[192:193], s[48:49], 0, v[192:193]
	s_waitcnt lgkmcnt(0)
	v_pk_mul_f32 v[28:29], v[28:29], v[158:159] op_sel_hi:[1,0]
	v_pk_mul_f32 v[30:31], v[30:31], v[158:159] op_sel_hi:[1,0]
	v_pk_mul_f32 v[24:25], v[24:25], v[158:159] op_sel_hi:[1,0]
	v_pk_mul_f32 v[26:27], v[26:27], v[158:159] op_sel_hi:[1,0]
	v_pk_mul_f32 v[20:21], v[20:21], v[158:159] op_sel_hi:[1,0]
	v_pk_mul_f32 v[22:23], v[22:23], v[158:159] op_sel_hi:[1,0]
	v_pk_mul_f32 v[16:17], v[16:17], v[158:159] op_sel_hi:[1,0]
	v_pk_mul_f32 v[18:19], v[18:19], v[158:159] op_sel_hi:[1,0]
	v_lshl_add_u64 v[146:147], v[192:193], 0, v[146:147]
	v_mul_f32_e32 v158, v117, v117
	v_mul_f32_e32 v159, v119, v119
	v_mul_f32_e32 v192, v115, v115
	v_fmac_f32_e32 v158, v116, v116
	v_fmac_f32_e32 v159, v118, v118
	v_fmac_f32_e32 v192, v114, v114
	s_waitcnt vmcnt(2)
	v_mov_b32_e32 v204, v154
	v_mov_b32_e32 v205, v155
	v_mov_b32_e32 v206, v156
	v_mov_b32_e32 v207, v157
	v_mov_b32_dpp v154, v188 row_ror:8 row_mask:0xf bank_mask:0xc
	v_mov_b32_dpp v155, v189 row_ror:8 row_mask:0xf bank_mask:0xc
	v_mov_b32_dpp v156, v190 row_ror:8 row_mask:0xf bank_mask:0xc
	v_mov_b32_dpp v157, v191 row_ror:8 row_mask:0xf bank_mask:0xc
	v_mov_b32_dpp v188, v204 row_ror:8 row_mask:0xf bank_mask:0x3
	v_mov_b32_dpp v189, v205 row_ror:8 row_mask:0xf bank_mask:0x3
	v_mov_b32_dpp v190, v206 row_ror:8 row_mask:0xf bank_mask:0x3
	v_mov_b32_dpp v191, v207 row_ror:8 row_mask:0xf bank_mask:0x3
	v_pk_fma_f32 v[30:31], v[134:135], v[30:31], v[156:157]
	v_pk_fma_f32 v[28:29], v[132:133], v[28:29], v[154:155]
	s_waitcnt vmcnt(2)
	v_pk_fma_f32 v[26:27], v[130:131], v[26:27], v[190:191]
	v_pk_fma_f32 v[24:25], v[128:129], v[24:25], v[188:189]
	s_waitcnt vmcnt(0)
;     __device__ __forceinline__ void run(const f32x4 (&v)[2][2][4][2], const Unit& u, int wr, int wc, int fr, int fq, PG8_LAS unsigned char* lds, int wid, int lane) const {
;     ...
;                 float s = 0.f;
; #pragma unroll
;                 for (int bj = 0; bj < 2; ++bj)
; #pragma unroll
;                     for (int n = 0; n < 2; ++n) { const f32x4 x = v[ai][bj][m][n]; s += (x[0] * x[0] + x[1] * x[1]) + (x[2] * x[2] + x[3] * x[3]); }
;                 s += __shfl_xor(s, 16); s += __shfl_xor(s, 32);
;                 if (fq == 0) P[(ai * HALF + wr * 64 + m * 16 + fr) * 4 + wc] = s;
;     __device__ __forceinline__ void fused(f32x4 (&acc)[2][2][4][2], const Unit& u, int wr, int wc, int fr, int fq, PG8_LAS unsigned char* lds, int wid, int lane) const {
;     ...
; #pragma unroll
;             for (int ai = 0; ai < 2; ++ai)
; #pragma unroll
;                 for (int m = 0; m < 4; ++m) { const int r = ai * HALF + wr * 64 + m * 16 + fr; const float rs = S[r]; const size_t off = (size_t)(row_off + u.pm * BM + r) * DM + col0;
; #pragma unroll
;                     for (int bj = 0; bj < 2; ++bj)
; #pragma unroll
;                         for (int n = 0; n < 2; ++n) { const f32x4 bs = __builtin_nontemporal_load((const f32x4*)(base + off + bj * HALF + n * 16)); acc[ai][bj][m][n] = bs + acc[ai][bj][m][n] * rs * g[bj][n]; }
;                     asm volatile("" : "+v"(acc[ai][0][m][0]), "+v"(acc[ai][0][m][1]), "+v"(acc[ai][1][m][0]), "+v"(acc[ai][1][m][1]));
;                     if (m & 1) asm volatile("" ::: "memory"); }
	v_mov_b32_e32 v204, v196
	v_mov_b32_e32 v205, v197
	v_mov_b32_e32 v206, v198
	v_mov_b32_e32 v207, v199
	v_mov_b32_dpp v196, v200 row_ror:8 row_mask:0xf bank_mask:0xc
	v_mov_b32_dpp v197, v201 row_ror:8 row_mask:0xf bank_mask:0xc
	v_mov_b32_dpp v198, v202 row_ror:8 row_mask:0xf bank_mask:0xc
	v_mov_b32_dpp v199, v203 row_ror:8 row_mask:0xf bank_mask:0xc
	v_mov_b32_dpp v200, v204 row_ror:8 row_mask:0xf bank_mask:0x3
	v_mov_b32_dpp v201, v205 row_ror:8 row_mask:0xf bank_mask:0x3
	v_mov_b32_dpp v202, v206 row_ror:8 row_mask:0xf bank_mask:0x3
	v_mov_b32_dpp v203, v207 row_ror:8 row_mask:0xf bank_mask:0x3
	v_pk_fma_f32 v[22:23], v[142:143], v[22:23], v[198:199]
	v_pk_fma_f32 v[20:21], v[140:141], v[20:21], v[196:197]
	s_waitcnt vmcnt(0)
	v_pk_fma_f32 v[18:19], v[138:139], v[18:19], v[202:203]
	v_pk_fma_f32 v[16:17], v[136:137], v[16:17], v[200:201]
	s_nop 0
	v_lshl_add_u64 v[214:215], v[146:147], 0, v[208:209]
	v_lshl_add_u64 v[212:213], v[214:215], 0, s[42:43]
	global_load_dwordx4 v[154:157], v[214:215], off nt
	global_load_dwordx4 v[188:191], v[212:213], off nt
	global_load_dwordx4 v[196:199], v[214:215], off offset:512 nt
	global_load_dwordx4 v[200:203], v[212:213], off offset:512 nt
	v_mul_f32_e32 v146, v127, v127
	v_mul_f32_e32 v147, v121, v121
	v_fmac_f32_e32 v146, v126, v126
	v_fmac_f32_e32 v147, v120, v120
	v_add_f32_e32 v145, v145, v146
	v_add_f32_e32 v146, v147, v149
	v_add_f32_e32 v147, v158, v159
	v_add_f32_e32 v145, v145, v146
	v_add_f32_e32 v149, v187, v192
	v_add_f32_e32 v145, v147, v145
	v_add_f32_e32 v145, v149, v145
	ds_bpermute_b32 v146, v150, v145
	ds_read_b32 v158, v160 offset:4800
	s_waitcnt lgkmcnt(1)
	v_add_f32_e32 v145, v145, v146
	ds_bpermute_b32 v146, v151, v145
	s_waitcnt lgkmcnt(1)
	v_pk_mul_f32 v[12:13], v[12:13], v[158:159] op_sel_hi:[1,0]
	v_pk_mul_f32 v[14:15], v[14:15], v[158:159] op_sel_hi:[1,0]
	v_pk_mul_f32 v[8:9], v[8:9], v[158:159] op_sel_hi:[1,0]
	v_pk_mul_f32 v[10:11], v[10:11], v[158:159] op_sel_hi:[1,0]
	v_pk_mul_f32 v[4:5], v[4:5], v[158:159] op_sel_hi:[1,0]
	v_pk_mul_f32 v[6:7], v[6:7], v[158:159] op_sel_hi:[1,0]
	v_pk_mul_f32 v[0:1], v[0:1], v[158:159] op_sel_hi:[1,0]
	v_pk_mul_f32 v[2:3], v[2:3], v[158:159] op_sel_hi:[1,0]
	s_waitcnt vmcnt(2)
	v_mov_b32_e32 v204, v154
	v_mov_b32_e32 v205, v155
	v_mov_b32_e32 v206, v156
	v_mov_b32_e32 v207, v157
	v_mov_b32_dpp v154, v188 row_ror:8 row_mask:0xf bank_mask:0xc
	v_mov_b32_dpp v155, v189 row_ror:8 row_mask:0xf bank_mask:0xc
	v_mov_b32_dpp v156, v190 row_ror:8 row_mask:0xf bank_mask:0xc
	v_mov_b32_dpp v157, v191 row_ror:8 row_mask:0xf bank_mask:0xc
	v_mov_b32_dpp v188, v204 row_ror:8 row_mask:0xf bank_mask:0x3
	v_mov_b32_dpp v189, v205 row_ror:8 row_mask:0xf bank_mask:0x3
	v_mov_b32_dpp v190, v206 row_ror:8 row_mask:0xf bank_mask:0x3
	v_mov_b32_dpp v191, v207 row_ror:8 row_mask:0xf bank_mask:0x3
	v_pk_fma_f32 v[14:15], v[134:135], v[14:15], v[156:157]
	v_pk_fma_f32 v[12:13], v[132:133], v[12:13], v[154:155]
	s_waitcnt vmcnt(2)
	v_pk_fma_f32 v[10:11], v[130:131], v[10:11], v[190:191]
	v_pk_fma_f32 v[8:9], v[128:129], v[8:9], v[188:189]
	s_waitcnt vmcnt(0)
	v_mov_b32_e32 v204, v196
	v_mov_b32_e32 v205, v197
	v_mov_b32_e32 v206, v198
	v_mov_b32_e32 v207, v199
	v_mov_b32_dpp v196, v200 row_ror:8 row_mask:0xf bank_mask:0xc
	v_mov_b32_dpp v197, v201 row_ror:8 row_mask:0xf bank_mask:0xc
	v_mov_b32_dpp v198, v202 row_ror:8 row_mask:0xf bank_mask:0xc
	v_mov_b32_dpp v199, v203 row_ror:8 row_mask:0xf bank_mask:0xc
	v_mov_b32_dpp v200, v204 row_ror:8 row_mask:0xf bank_mask:0x3
	v_mov_b32_dpp v201, v205 row_ror:8 row_mask:0xf bank_mask:0x3
	v_mov_b32_dpp v202, v206 row_ror:8 row_mask:0xf bank_mask:0x3
	v_mov_b32_dpp v203, v207 row_ror:8 row_mask:0xf bank_mask:0x3
	v_pk_fma_f32 v[6:7], v[142:143], v[6:7], v[198:199]
	v_pk_fma_f32 v[4:5], v[140:141], v[4:5], v[196:197]
	s_waitcnt vmcnt(0)
	v_pk_fma_f32 v[2:3], v[138:139], v[2:3], v[202:203]
	v_pk_fma_f32 v[0:1], v[136:137], v[0:1], v[200:201]
	s_nop 0
	s_and_saveexec_b64 s[48:49], s[6:7]
	s_cbranch_execz .LBB0_792
	s_lshl_b32 s18, s68, 10
	s_add_i32 s18, s58, s18
	v_lshl_add_u32 v128, v148, 4, s18
	s_waitcnt lgkmcnt(0)
	v_add_f32_e32 v129, v145, v146
	ds_write_b32 v128, v129
